# P6: next-tile LDS-DMA waits deferred past the epilogue (phase-4 vmcnt skipped on last K-iteration, row-sum loads hoisted, vmcnt+barrier at epilogue end)
# speedup vs baseline: 1.0125x; 1.0125x over previous
;     ...
; #pragma unroll
;         for (int a = 0; a < 2; ++a)
; #pragma unroll
;             for (int b = 0; b < 2; ++b)
; #pragma unroll
;                 for (int m = 0; m < 4; ++m)
; #pragma unroll
;                     for (int n = 0; n < 2; ++n) acc[a][b][m][n] = (f32x4){0.f, 0.f, 0.f, 0.f};
; template <int NS> DI void row_scales(const float* rsp, float inv, int grow0, float (&rs)[8]) {
; #pragma unroll
;     for (int it = 0; it < 8; ++it) rs[it] = rsp[grow0 + (it >> 2) * 128 + (it & 3) * 16];
.LBB0_1340:
	s_ashr_i32 s23, s22, 31
	s_lshl_b64 s[24:25], s[22:23], 19
	s_add_u32 s24, s15, s24
	s_addc_u32 s25, s40, s25
	s_and_b64 s[26:27], s[0:1], exec
	s_cselect_b32 s23, s25, s35
	s_cselect_b32 s58, s24, s34
	s_ashr_i32 s21, s20, 31
	s_lshl_b64 s[26:27], s[20:21], 19
	s_add_u32 s26, s41, s26
	s_addc_u32 s27, s42, s27
	s_and_b64 s[38:39], s[0:1], exec
	s_cselect_b32 s21, s27, s37
	s_cselect_b32 s59, s26, s36
	s_add_u32 s34, s34, 0x40080
	s_addc_u32 s35, s35, 0
	s_add_u32 s60, s36, 0x100
	v_mov_b32_e32 v0, 0
	s_addc_u32 s61, s37, 0
	s_mov_b32 s62, -2
	v_mov_b32_e32 v1, v0
	v_mov_b32_e32 v2, v0
	v_mov_b32_e32 v3, v0
	v_mov_b32_e32 v4, v0
	v_mov_b32_e32 v5, v0
	v_mov_b32_e32 v6, v0
	v_mov_b32_e32 v7, v0
	v_mov_b32_e32 v16, v0
	v_mov_b32_e32 v17, v0
	v_mov_b32_e32 v18, v0
	v_mov_b32_e32 v19, v0
	v_mov_b32_e32 v20, v0
	v_mov_b32_e32 v21, v0
	v_mov_b32_e32 v22, v0
	v_mov_b32_e32 v23, v0
	v_mov_b32_e32 v32, v0
	v_mov_b32_e32 v33, v0
	v_mov_b32_e32 v34, v0
	v_mov_b32_e32 v35, v0
	v_mov_b32_e32 v36, v0
	v_mov_b32_e32 v37, v0
	v_mov_b32_e32 v38, v0
	v_mov_b32_e32 v39, v0
	v_mov_b32_e32 v48, v0
	v_mov_b32_e32 v49, v0
	v_mov_b32_e32 v50, v0
	v_mov_b32_e32 v51, v0
	v_mov_b32_e32 v52, v0
	v_mov_b32_e32 v53, v0
	v_mov_b32_e32 v54, v0
	v_mov_b32_e32 v55, v0
	v_mov_b32_e32 v8, v0
	v_mov_b32_e32 v9, v0
	v_mov_b32_e32 v10, v0
	v_mov_b32_e32 v11, v0
	v_mov_b32_e32 v12, v0
	v_mov_b32_e32 v13, v0
	v_mov_b32_e32 v14, v0
	v_mov_b32_e32 v15, v0
	v_mov_b32_e32 v24, v0
	v_mov_b32_e32 v25, v0
	v_mov_b32_e32 v26, v0
	v_mov_b32_e32 v27, v0
	v_mov_b32_e32 v28, v0
	v_mov_b32_e32 v29, v0
	v_mov_b32_e32 v30, v0
	v_mov_b32_e32 v31, v0
	v_mov_b32_e32 v40, v0
	v_mov_b32_e32 v41, v0
	v_mov_b32_e32 v42, v0
	v_mov_b32_e32 v43, v0
	v_mov_b32_e32 v44, v0
	v_mov_b32_e32 v45, v0
	v_mov_b32_e32 v46, v0
	v_mov_b32_e32 v47, v0
	v_mov_b32_e32 v56, v0
	v_mov_b32_e32 v57, v0
	v_mov_b32_e32 v58, v0
	v_mov_b32_e32 v59, v0
	v_mov_b32_e32 v60, v0
	v_mov_b32_e32 v61, v0
	v_mov_b32_e32 v62, v0
	v_mov_b32_e32 v63, v0
	v_mov_b32_e32 v64, v0
	v_mov_b32_e32 v65, v0
	v_mov_b32_e32 v66, v0
	v_mov_b32_e32 v67, v0
	v_mov_b32_e32 v68, v0
	v_mov_b32_e32 v69, v0
	v_mov_b32_e32 v70, v0
	v_mov_b32_e32 v71, v0
	v_mov_b32_e32 v80, v0
	v_mov_b32_e32 v81, v0
	v_mov_b32_e32 v82, v0
	v_mov_b32_e32 v83, v0
	v_mov_b32_e32 v84, v0
	v_mov_b32_e32 v85, v0
	v_mov_b32_e32 v86, v0
	v_mov_b32_e32 v87, v0
	v_mov_b32_e32 v96, v0
	v_mov_b32_e32 v97, v0
	v_mov_b32_e32 v98, v0
	v_mov_b32_e32 v99, v0
	v_mov_b32_e32 v100, v0
	v_mov_b32_e32 v101, v0
	v_mov_b32_e32 v102, v0
	v_mov_b32_e32 v103, v0
	v_mov_b32_e32 v112, v0
	v_mov_b32_e32 v113, v0
	v_mov_b32_e32 v114, v0
	v_mov_b32_e32 v115, v0
	v_mov_b32_e32 v116, v0
	v_mov_b32_e32 v117, v0
	v_mov_b32_e32 v118, v0
	v_mov_b32_e32 v119, v0
	v_mov_b32_e32 v72, v0
	v_mov_b32_e32 v73, v0
	v_mov_b32_e32 v74, v0
	v_mov_b32_e32 v75, v0
	v_mov_b32_e32 v76, v0
	v_mov_b32_e32 v77, v0
	v_mov_b32_e32 v78, v0
	v_mov_b32_e32 v79, v0
	v_mov_b32_e32 v88, v0
	v_mov_b32_e32 v89, v0
	v_mov_b32_e32 v90, v0
	v_mov_b32_e32 v91, v0
	v_mov_b32_e32 v92, v0
	v_mov_b32_e32 v93, v0
	v_mov_b32_e32 v94, v0
	v_mov_b32_e32 v95, v0
	v_mov_b32_e32 v104, v0
	v_mov_b32_e32 v105, v0
	v_mov_b32_e32 v106, v0
	v_mov_b32_e32 v107, v0
	v_mov_b32_e32 v108, v0
	v_mov_b32_e32 v109, v0
	v_mov_b32_e32 v110, v0
	v_mov_b32_e32 v111, v0
	v_mov_b32_e32 v120, v0
	v_mov_b32_e32 v121, v0
	v_mov_b32_e32 v122, v0
	v_mov_b32_e32 v123, v0
	v_mov_b32_e32 v124, v0
	v_mov_b32_e32 v125, v0
	v_mov_b32_e32 v126, v0
	v_mov_b32_e32 v127, v0
	v_mbcnt_lo_u32_b32 v236, -1, 0
	v_mbcnt_hi_u32_b32 v236, -1, v236
	s_lshl_b32 s64, s28, 8
	s_add_i32 s64, s64, s50
	v_and_or_b32 v236, v236, 15, s64
	v_ashrrev_i32_e32 v237, 31, v236
	v_lshl_add_u64 v[236:237], v[236:237], 2, s[6:7]
	global_load_dword v228, v[236:237], off
	global_load_dword v229, v[236:237], off offset:64
	global_load_dword v230, v[236:237], off offset:128
	global_load_dword v231, v[236:237], off offset:192
	global_load_dword v233, v[236:237], off offset:512
	global_load_dword v234, v[236:237], off offset:576
	global_load_dword v235, v[236:237], off offset:640
	global_load_dword v238, v[236:237], off offset:704
.LBB0_1341:
	ds_read_b128 v[144:147], v151
	ds_read_b128 v[160:163], v151 offset:1024
	ds_read_b128 v[164:167], v151 offset:2048
	ds_read_b128 v[168:171], v151 offset:3072
	ds_read_b128 v[172:175], v153
	ds_read_b128 v[176:179], v153 offset:1024
	ds_read_b128 v[180:183], v153 offset:2048
	ds_read_b128 v[184:187], v153 offset:3072
	s_add_u32 s36, s34, 0xfffc0080
	s_addc_u32 s37, s35, -1
	s_cmp_eq_u32 s62, 12
	s_cselect_b32 s39, s23, s37
	s_cselect_b32 s38, s58, s36
	s_cselect_b32 s37, s21, s61
	s_cselect_b32 s36, s59, s60
	v_lshl_add_u64 v[154:155], s[34:35], 0, v[136:137]
	s_add_i32 m0, s29, 0xc000
	ds_read_b128 v[188:191], v157
	ds_read_b128 v[192:195], v157 offset:1024
	ds_read_b128 v[196:199], v157 offset:2048
	ds_read_b128 v[200:203], v157 offset:3072
	ds_read_b128 v[204:207], v157 offset:4096
	ds_read_b128 v[208:211], v157 offset:5120
	ds_read_b128 v[212:215], v157 offset:6144
	ds_read_b128 v[216:219], v157 offset:7168
	global_load_lds_dwordx4 v[154:155], off
	v_lshl_add_u64 v[154:155], s[34:35], 0, v[138:139]
	s_add_i32 m0, s29, 0xe000
	s_nop 0
	global_load_lds_dwordx4 v[154:155], off
	s_waitcnt vmcnt(8)
	s_waitcnt lgkmcnt(0)
	s_barrier
; #define PG8_STAGE(bufoff, gbase, voff) do { _Pragma("unroll") for (int _i = 0; _i < 2; ++_i) \
;         __builtin_amdgcn_global_load_lds((const unsigned*)((const char*)(gbase) + (voff)[_i]), (PG8_LAS unsigned*)(lds + (bufoff) + ldsw + _i * 8192), 16, 0, 0); } while (0)
; #define PG8_LDA(dst, b, h) do { _Pragma("unroll") for (int m = 0; m < 4; ++m) _Pragma("unroll") for (int k = 0; k < 2; ++k) dst[m][k] = *(const PG8_LAS bf16x8*)(lds + PG8_SA(b, h) + aoff + m * 2048 + k * 1024); } while (0)
; #define PG8_MMA(ai, bj, At, Bt) do { __builtin_amdgcn_s_setprio(1); _Pragma("unroll") for (int m = 0; m < 4; ++m) _Pragma("unroll") for (int n = 0; n < 2; ++n) _Pragma("unroll") for (int k = 0; k < 2; ++k) \
;         acc[ai][bj][m][n] = __builtin_amdgcn_mfma_f32_16x16x32_bf16(Bt[n][k], At[m][k], acc[ai][bj][m][n], 0, 0, 0); __builtin_amdgcn_s_setprio(0); } while (0)
; #define PG8_WAIT_V(n) asm volatile("s_waitcnt vmcnt(" #n ")" ::: "memory")
; #define PG8_WAIT_L(n) asm volatile("s_waitcnt lgkmcnt(" #n ")" ::: "memory")
; #define PG8_BAR __builtin_amdgcn_s_barrier()
; #define PG8_SCHED __builtin_amdgcn_sched_barrier(0)
;     ...
;             PG8_WAIT_V(8); PG8_WAIT_L(0); PG8_BAR; PG8_MMA(0, 0, At, B0); PG8_MMA(0, 1, At, B1); PG8_BAR; PG8_SCHED;
;             PG8_LDA(At, 0, 1); PG8_STAGE(PG8_SB(0, 0), b2, voffB); PG8_STAGE(PG8_SB(0, 1), b2 + hstepB, voffB); PG8_STAGE(PG8_SA(0, 0), a2, voffA);
;             PG8_WAIT_V(8); PG8_WAIT_L(0); PG8_BAR; PG8_MMA(1, 0, At, B0); PG8_MMA(1, 1, At, B1); PG8_BAR; PG8_SCHED;
	s_setprio 1
	s_waitcnt lgkmcnt(0)
	v_mfma_f32_16x16x32_bf16 v[124:127], v[144:147], v[188:191], v[124:127]
	v_mfma_f32_16x16x32_bf16 v[120:123], v[164:167], v[188:191], v[120:123]
	v_mfma_f32_16x16x32_bf16 v[108:111], v[144:147], v[196:199], v[108:111]
	v_mfma_f32_16x16x32_bf16 v[104:107], v[164:167], v[196:199], v[104:107]
	v_mfma_f32_16x16x32_bf16 v[92:95], v[144:147], v[204:207], v[92:95]
	v_mfma_f32_16x16x32_bf16 v[88:91], v[164:167], v[204:207], v[88:91]
	v_mfma_f32_16x16x32_bf16 v[76:79], v[144:147], v[212:215], v[76:79]
	v_mfma_f32_16x16x32_bf16 v[72:75], v[164:167], v[212:215], v[72:75]
	v_mfma_f32_16x16x32_bf16 v[124:127], v[160:163], v[192:195], v[124:127]
	v_mfma_f32_16x16x32_bf16 v[120:123], v[168:171], v[192:195], v[120:123]
	v_mfma_f32_16x16x32_bf16 v[108:111], v[160:163], v[200:203], v[108:111]
	v_mfma_f32_16x16x32_bf16 v[104:107], v[168:171], v[200:203], v[104:107]
	v_mfma_f32_16x16x32_bf16 v[92:95], v[160:163], v[208:211], v[92:95]
	v_mfma_f32_16x16x32_bf16 v[88:91], v[168:171], v[208:211], v[88:91]
	v_mfma_f32_16x16x32_bf16 v[76:79], v[160:163], v[216:219], v[76:79]
	v_mfma_f32_16x16x32_bf16 v[72:75], v[168:171], v[216:219], v[72:75]
	s_setprio 0
	s_setprio 1
	v_mfma_f32_16x16x32_bf16 v[116:119], v[172:175], v[188:191], v[116:119]
	v_mfma_f32_16x16x32_bf16 v[112:115], v[180:183], v[188:191], v[112:115]
	v_mfma_f32_16x16x32_bf16 v[100:103], v[172:175], v[196:199], v[100:103]
	v_mfma_f32_16x16x32_bf16 v[96:99], v[180:183], v[196:199], v[96:99]
	v_mfma_f32_16x16x32_bf16 v[84:87], v[172:175], v[204:207], v[84:87]
	v_mfma_f32_16x16x32_bf16 v[80:83], v[180:183], v[204:207], v[80:83]
	v_mfma_f32_16x16x32_bf16 v[68:71], v[172:175], v[212:215], v[68:71]
	v_mfma_f32_16x16x32_bf16 v[64:67], v[180:183], v[212:215], v[64:67]
	v_mfma_f32_16x16x32_bf16 v[116:119], v[176:179], v[192:195], v[116:119]
	v_mfma_f32_16x16x32_bf16 v[112:115], v[184:187], v[192:195], v[112:115]
	v_mfma_f32_16x16x32_bf16 v[100:103], v[176:179], v[200:203], v[100:103]
	v_mfma_f32_16x16x32_bf16 v[96:99], v[184:187], v[200:203], v[96:99]
	v_mfma_f32_16x16x32_bf16 v[84:87], v[176:179], v[208:211], v[84:87]
	v_mfma_f32_16x16x32_bf16 v[80:83], v[184:187], v[208:211], v[80:83]
	v_mfma_f32_16x16x32_bf16 v[68:71], v[176:179], v[216:219], v[68:71]
	v_mfma_f32_16x16x32_bf16 v[64:67], v[184:187], v[216:219], v[64:67]
	s_setprio 0
	s_barrier
	s_add_i32 s48, s54, s43
	v_lshl_add_u64 v[154:155], s[36:37], 0, v[132:133]
	s_mov_b32 m0, s48
	ds_read_b128 v[188:191], v157 offset:16384
	ds_read_b128 v[192:195], v157 offset:17408
	ds_read_b128 v[196:199], v157 offset:18432
	ds_read_b128 v[200:203], v157 offset:19456
	ds_read_b128 v[204:207], v157 offset:20480
	ds_read_b128 v[208:211], v157 offset:21504
	ds_read_b128 v[212:215], v157 offset:22528
	ds_read_b128 v[216:219], v157 offset:23552
	global_load_lds_dwordx4 v[154:155], off
	s_add_i32 m0, s48, 0x2000
	s_add_u32 s48, s36, 0x40000
	v_lshl_add_u64 v[220:221], s[36:37], 0, v[128:129]
	s_addc_u32 s49, s37, 0
	s_add_i32 s63, s55, s43
	global_load_lds_dwordx4 v[220:221], off
	v_lshl_add_u64 v[222:223], s[48:49], 0, v[132:133]
	s_mov_b32 m0, s63
	v_lshl_add_u64 v[224:225], s[38:39], 0, v[130:131]
	global_load_lds_dwordx4 v[222:223], off
	v_lshl_add_u64 v[222:223], s[48:49], 0, v[128:129]
	s_add_i32 m0, s63, 0x2000
	s_nop 0
	global_load_lds_dwordx4 v[222:223], off
	v_lshl_add_u64 v[222:223], s[38:39], 0, v[134:135]
	s_mov_b32 m0, s29
	s_nop 0
	global_load_lds_dwordx4 v[222:223], off
	s_mov_b32 m0, s44
	s_nop 0
	global_load_lds_dwordx4 v[224:225], off
	s_waitcnt vmcnt(8)
	s_waitcnt lgkmcnt(0)
	s_barrier
	s_setprio 1
	s_waitcnt lgkmcnt(0)
	v_mfma_f32_16x16x32_bf16 v[60:63], v[144:147], v[188:191], v[60:63]
	v_mfma_f32_16x16x32_bf16 v[56:59], v[164:167], v[188:191], v[56:59]
	v_mfma_f32_16x16x32_bf16 v[44:47], v[144:147], v[196:199], v[44:47]
	v_mfma_f32_16x16x32_bf16 v[40:43], v[164:167], v[196:199], v[40:43]
	v_mfma_f32_16x16x32_bf16 v[28:31], v[144:147], v[204:207], v[28:31]
	v_mfma_f32_16x16x32_bf16 v[24:27], v[164:167], v[204:207], v[24:27]
	v_mfma_f32_16x16x32_bf16 v[12:15], v[144:147], v[212:215], v[12:15]
	v_mfma_f32_16x16x32_bf16 v[8:11], v[164:167], v[212:215], v[8:11]
	v_mfma_f32_16x16x32_bf16 v[60:63], v[160:163], v[192:195], v[60:63]
	v_mfma_f32_16x16x32_bf16 v[56:59], v[168:171], v[192:195], v[56:59]
	v_mfma_f32_16x16x32_bf16 v[44:47], v[160:163], v[200:203], v[44:47]
	v_mfma_f32_16x16x32_bf16 v[40:43], v[168:171], v[200:203], v[40:43]
	v_mfma_f32_16x16x32_bf16 v[28:31], v[160:163], v[208:211], v[28:31]
	v_mfma_f32_16x16x32_bf16 v[24:27], v[168:171], v[208:211], v[24:27]
	v_mfma_f32_16x16x32_bf16 v[12:15], v[160:163], v[216:219], v[12:15]
	v_mfma_f32_16x16x32_bf16 v[8:11], v[168:171], v[216:219], v[8:11]
	s_setprio 0
	s_setprio 1
	v_mfma_f32_16x16x32_bf16 v[52:55], v[172:175], v[188:191], v[52:55]
	v_mfma_f32_16x16x32_bf16 v[48:51], v[180:183], v[188:191], v[48:51]
	v_mfma_f32_16x16x32_bf16 v[36:39], v[172:175], v[196:199], v[36:39]
	v_mfma_f32_16x16x32_bf16 v[32:35], v[180:183], v[196:199], v[32:35]
	v_mfma_f32_16x16x32_bf16 v[20:23], v[172:175], v[204:207], v[20:23]
	v_mfma_f32_16x16x32_bf16 v[16:19], v[180:183], v[204:207], v[16:19]
	v_mfma_f32_16x16x32_bf16 v[4:7], v[172:175], v[212:215], v[4:7]
	v_mfma_f32_16x16x32_bf16 v[0:3], v[180:183], v[212:215], v[0:3]
	v_mfma_f32_16x16x32_bf16 v[52:55], v[176:179], v[192:195], v[52:55]
	v_mfma_f32_16x16x32_bf16 v[48:51], v[184:187], v[192:195], v[48:51]
	v_mfma_f32_16x16x32_bf16 v[36:39], v[176:179], v[200:203], v[36:39]
	v_mfma_f32_16x16x32_bf16 v[32:35], v[184:187], v[200:203], v[32:35]
	v_mfma_f32_16x16x32_bf16 v[20:23], v[176:179], v[208:211], v[20:23]
	v_mfma_f32_16x16x32_bf16 v[16:19], v[184:187], v[208:211], v[16:19]
	v_mfma_f32_16x16x32_bf16 v[4:7], v[176:179], v[216:219], v[4:7]
	v_mfma_f32_16x16x32_bf16 v[0:3], v[184:187], v[216:219], v[0:3]
	s_setprio 0
	s_barrier
; #define PG8_STAGE(bufoff, gbase, voff) do { _Pragma("unroll") for (int _i = 0; _i < 2; ++_i) \
;         __builtin_amdgcn_global_load_lds((const unsigned*)((const char*)(gbase) + (voff)[_i]), (PG8_LAS unsigned*)(lds + (bufoff) + ldsw + _i * 8192), 16, 0, 0); } while (0)
; #define PG8_LDA(dst, b, h) do { _Pragma("unroll") for (int m = 0; m < 4; ++m) _Pragma("unroll") for (int k = 0; k < 2; ++k) dst[m][k] = *(const PG8_LAS bf16x8*)(lds + PG8_SA(b, h) + aoff + m * 2048 + k * 1024); } while (0)
; #define PG8_LDB(dst, b, h) do { _Pragma("unroll") for (int n = 0; n < 2; ++n) _Pragma("unroll") for (int k = 0; k < 2; ++k) dst[n][k] = *(const PG8_LAS bf16x8*)(lds + PG8_SB(b, h) + boff + n * 2048 + k * 1024); } while (0)
; #define PG8_MMA(ai, bj, At, Bt) do { __builtin_amdgcn_s_setprio(1); _Pragma("unroll") for (int m = 0; m < 4; ++m) _Pragma("unroll") for (int n = 0; n < 2; ++n) _Pragma("unroll") for (int k = 0; k < 2; ++k) \
;         acc[ai][bj][m][n] = __builtin_amdgcn_mfma_f32_16x16x32_bf16(Bt[n][k], At[m][k], acc[ai][bj][m][n], 0, 0, 0); __builtin_amdgcn_s_setprio(0); } while (0)
; #define PG8_WAIT_V(n) asm volatile("s_waitcnt vmcnt(" #n ")" ::: "memory")
; #define PG8_WAIT_L(n) asm volatile("s_waitcnt lgkmcnt(" #n ")" ::: "memory")
; #define PG8_BAR __builtin_amdgcn_s_barrier()
; #define PG8_SCHED __builtin_amdgcn_sched_barrier(0)
;     ...
;             PG8_LDB(B0, 1, 0); PG8_LDB(B1, 1, 1); PG8_SCHED; PG8_LDA(At, 1, 0); PG8_STAGE(PG8_SA(0, 1), a2 + hstepA, voffA);
;             PG8_WAIT_V(8); PG8_WAIT_L(0); PG8_BAR; PG8_MMA(0, 0, At, B0); PG8_MMA(0, 1, At, B1); PG8_BAR; PG8_SCHED;
;             PG8_LDA(At, 1, 1); PG8_STAGE(PG8_SB(1, 0), b3, voffB); PG8_STAGE(PG8_SB(1, 1), b3 + hstepB, voffB); PG8_STAGE(PG8_SA(1, 0), a3, voffA);
	s_add_i32 s48, 0, 0x18000
	v_add_u32_e32 v148, s48, v149
	s_add_i32 s49, 0, 0x1c000
	ds_read_b128 v[144:147], v148
	ds_read_b128 v[160:163], v148 offset:1024
	ds_read_b128 v[164:167], v148 offset:2048
	ds_read_b128 v[168:171], v148 offset:3072
	v_add_u32_e32 v148, s49, v149
	ds_read_b128 v[172:175], v148
	ds_read_b128 v[176:179], v148 offset:1024
	ds_read_b128 v[180:183], v148 offset:2048
	ds_read_b128 v[184:187], v148 offset:3072
	s_add_u32 s38, s38, 0x40000
	s_addc_u32 s39, s39, 0
	s_mov_b32 m0, s45
	v_lshl_add_u64 v[226:227], s[38:39], 0, v[134:135]
	ds_read_b128 v[188:191], v157 offset:32768
	ds_read_b128 v[192:195], v157 offset:33792
	ds_read_b128 v[196:199], v157 offset:34816
	ds_read_b128 v[200:203], v157 offset:35840
	ds_read_b128 v[204:207], v157 offset:36864
	ds_read_b128 v[208:211], v157 offset:37888
	ds_read_b128 v[212:215], v157 offset:38912
	ds_read_b128 v[216:219], v157 offset:39936
	global_load_lds_dwordx4 v[226:227], off
	v_lshl_add_u64 v[226:227], s[38:39], 0, v[130:131]
	s_mov_b32 m0, s46
	s_nop 0
	global_load_lds_dwordx4 v[226:227], off
	s_waitcnt vmcnt(8)
	s_waitcnt lgkmcnt(0)
	s_barrier
	s_setprio 1
	s_waitcnt lgkmcnt(0)
	v_mfma_f32_16x16x32_bf16 v[124:127], v[144:147], v[188:191], v[124:127]
	v_mfma_f32_16x16x32_bf16 v[120:123], v[164:167], v[188:191], v[120:123]
	v_mfma_f32_16x16x32_bf16 v[108:111], v[144:147], v[196:199], v[108:111]
	v_mfma_f32_16x16x32_bf16 v[104:107], v[164:167], v[196:199], v[104:107]
	v_mfma_f32_16x16x32_bf16 v[92:95], v[144:147], v[204:207], v[92:95]
	v_mfma_f32_16x16x32_bf16 v[88:91], v[164:167], v[204:207], v[88:91]
	v_mfma_f32_16x16x32_bf16 v[76:79], v[144:147], v[212:215], v[76:79]
	v_mfma_f32_16x16x32_bf16 v[72:75], v[164:167], v[212:215], v[72:75]
	v_mfma_f32_16x16x32_bf16 v[124:127], v[160:163], v[192:195], v[124:127]
	v_mfma_f32_16x16x32_bf16 v[120:123], v[168:171], v[192:195], v[120:123]
	v_mfma_f32_16x16x32_bf16 v[108:111], v[160:163], v[200:203], v[108:111]
	v_mfma_f32_16x16x32_bf16 v[104:107], v[168:171], v[200:203], v[104:107]
	v_mfma_f32_16x16x32_bf16 v[92:95], v[160:163], v[208:211], v[92:95]
	v_mfma_f32_16x16x32_bf16 v[88:91], v[168:171], v[208:211], v[88:91]
	v_mfma_f32_16x16x32_bf16 v[76:79], v[160:163], v[216:219], v[76:79]
	v_mfma_f32_16x16x32_bf16 v[72:75], v[168:171], v[216:219], v[72:75]
	s_setprio 0
	s_setprio 1
	v_mfma_f32_16x16x32_bf16 v[116:119], v[172:175], v[188:191], v[116:119]
	v_mfma_f32_16x16x32_bf16 v[112:115], v[180:183], v[188:191], v[112:115]
	v_mfma_f32_16x16x32_bf16 v[100:103], v[172:175], v[196:199], v[100:103]
	v_mfma_f32_16x16x32_bf16 v[96:99], v[180:183], v[196:199], v[96:99]
	v_mfma_f32_16x16x32_bf16 v[84:87], v[172:175], v[204:207], v[84:87]
	v_mfma_f32_16x16x32_bf16 v[80:83], v[180:183], v[204:207], v[80:83]
	v_mfma_f32_16x16x32_bf16 v[68:71], v[172:175], v[212:215], v[68:71]
	v_mfma_f32_16x16x32_bf16 v[64:67], v[180:183], v[212:215], v[64:67]
	v_mfma_f32_16x16x32_bf16 v[116:119], v[176:179], v[192:195], v[116:119]
	v_mfma_f32_16x16x32_bf16 v[112:115], v[184:187], v[192:195], v[112:115]
	v_mfma_f32_16x16x32_bf16 v[100:103], v[176:179], v[200:203], v[100:103]
	v_mfma_f32_16x16x32_bf16 v[96:99], v[184:187], v[200:203], v[96:99]
	v_mfma_f32_16x16x32_bf16 v[84:87], v[176:179], v[208:211], v[84:87]
	v_mfma_f32_16x16x32_bf16 v[80:83], v[184:187], v[208:211], v[80:83]
	v_mfma_f32_16x16x32_bf16 v[68:71], v[176:179], v[216:219], v[68:71]
	v_mfma_f32_16x16x32_bf16 v[64:67], v[184:187], v[216:219], v[64:67]
	s_setprio 0
	s_barrier
	s_add_i32 s38, s48, s43
	v_lshl_add_u64 v[154:155], v[154:155], 0, s[10:11]
	s_mov_b32 m0, s38
	ds_read_b128 v[188:191], v157 offset:49152
	ds_read_b128 v[192:195], v157 offset:50176
	ds_read_b128 v[196:199], v157 offset:51200
	ds_read_b128 v[200:203], v157 offset:52224
	ds_read_b128 v[204:207], v157 offset:53248
	ds_read_b128 v[208:211], v157 offset:54272
	ds_read_b128 v[212:215], v157 offset:55296
	ds_read_b128 v[216:219], v157 offset:56320
	global_load_lds_dwordx4 v[154:155], off
	s_add_i32 m0, s38, 0x2000
	s_add_u32 s36, s36, 0x40080
	v_lshl_add_u64 v[154:155], v[220:221], 0, s[10:11]
	s_addc_u32 s37, s37, 0
	s_add_i32 s38, s49, s43
	global_load_lds_dwordx4 v[154:155], off
	v_lshl_add_u64 v[154:155], s[36:37], 0, v[132:133]
	s_mov_b32 m0, s38
	s_nop 0
	global_load_lds_dwordx4 v[154:155], off
	v_lshl_add_u64 v[154:155], s[36:37], 0, v[128:129]
	s_add_i32 m0, s38, 0x2000
	s_nop 0
	global_load_lds_dwordx4 v[154:155], off
	v_lshl_add_u64 v[154:155], v[222:223], 0, s[10:11]
	s_mov_b32 m0, s52
	s_nop 0
	global_load_lds_dwordx4 v[154:155], off
	v_lshl_add_u64 v[154:155], v[224:225], 0, s[10:11]
	s_mov_b32 m0, s53
	s_nop 0
	global_load_lds_dwordx4 v[154:155], off
	s_cmp_eq_u32 s62, 12
	s_cbranch_scc1 .Lnx_skipw
	s_waitcnt vmcnt(8)
; DI void st8(bf16_t* p, const float (&v)[8]) { u32x4 w; w.x = cvtpk(v[0], v[1]); w.y = cvtpk(v[2], v[3]); w.z = cvtpk(v[4], v[5]); w.w = cvtpk(v[6], v[7]); *(u32x4*)p = w; }
; #define ACC8(v, ai, bj, m, s) do { const f32x4 a_ = acc[ai][bj][m][0] * (s), b_ = acc[ai][bj][m][1] * (s); v[0] = a_[0]; v[1] = a_[1]; v[2] = a_[2]; v[3] = a_[3]; v[4] = b_[0]; v[5] = b_[1]; v[6] = b_[2]; v[7] = b_[3]; } while (0)
; #define ITLOOP _Pragma("unroll") for (int it = 0; it < 8; ++it)
; #define BJLOOP _Pragma("unroll") for (int bj = 0; bj < 2; ++bj)
; #define SBE() __builtin_amdgcn_sched_barrier(0)
; template <int NS> DI void row_scales(const float* rsp, float inv, int grow0, float (&rs)[8]) {
; #pragma unroll
;     for (int it = 0; it < 8; ++it) rs[it] = rsp[grow0 + (it >> 2) * 128 + (it & 3) * 16];
;     if (NS != 0) {
; #pragma unroll
;         for (int it = 0; it < 8; ++it) rs[it] = __builtin_amdgcn_rsqf(rs[it] * inv + EPSN); }
;     DI void operator()(const AccT& acc, const pg8::Unit& u, int wr, int wc, int fr_in, int fq_in) const {
;     ...
;         if (KIND == K_FF1) {
;             float rs[8]; row_scales<1>(b.ssq2, 1.0f / 1024.0f, grow0, rs);
;             ITLOOP { BJLOOP { float v[8]; ACC8(v, IT_AI, bj, IT_M, rs[it]);
; #pragma unroll
;                 for (int e = 0; e < 8; ++e) { const float t = fmaxf(v[e], 0.f); v[e] = t * t; }
;                 st8(b.hdn + IT_ROW * 4096 + tc0 + bj * 128, v); } SBE(); }
.Lnx_skipw:
	s_waitcnt lgkmcnt(0)
	s_barrier
	s_setprio 1
	s_waitcnt lgkmcnt(0)
	v_mfma_f32_16x16x32_bf16 v[60:63], v[144:147], v[188:191], v[60:63]
	v_mfma_f32_16x16x32_bf16 v[56:59], v[164:167], v[188:191], v[56:59]
	v_mfma_f32_16x16x32_bf16 v[44:47], v[144:147], v[196:199], v[44:47]
	v_mfma_f32_16x16x32_bf16 v[40:43], v[164:167], v[196:199], v[40:43]
	v_mfma_f32_16x16x32_bf16 v[28:31], v[144:147], v[204:207], v[28:31]
	v_mfma_f32_16x16x32_bf16 v[24:27], v[164:167], v[204:207], v[24:27]
	v_mfma_f32_16x16x32_bf16 v[12:15], v[144:147], v[212:215], v[12:15]
	v_mfma_f32_16x16x32_bf16 v[8:11], v[164:167], v[212:215], v[8:11]
	v_mfma_f32_16x16x32_bf16 v[60:63], v[160:163], v[192:195], v[60:63]
	v_mfma_f32_16x16x32_bf16 v[56:59], v[168:171], v[192:195], v[56:59]
	v_mfma_f32_16x16x32_bf16 v[44:47], v[160:163], v[200:203], v[44:47]
	v_mfma_f32_16x16x32_bf16 v[40:43], v[168:171], v[200:203], v[40:43]
	v_mfma_f32_16x16x32_bf16 v[28:31], v[160:163], v[208:211], v[28:31]
	v_mfma_f32_16x16x32_bf16 v[24:27], v[168:171], v[208:211], v[24:27]
	v_mfma_f32_16x16x32_bf16 v[12:15], v[160:163], v[216:219], v[12:15]
	v_mfma_f32_16x16x32_bf16 v[8:11], v[168:171], v[216:219], v[8:11]
	s_setprio 0
	s_setprio 1
	v_mfma_f32_16x16x32_bf16 v[52:55], v[172:175], v[188:191], v[52:55]
	v_mfma_f32_16x16x32_bf16 v[48:51], v[180:183], v[188:191], v[48:51]
	v_mfma_f32_16x16x32_bf16 v[36:39], v[172:175], v[196:199], v[36:39]
	v_mfma_f32_16x16x32_bf16 v[32:35], v[180:183], v[196:199], v[32:35]
	v_mfma_f32_16x16x32_bf16 v[20:23], v[172:175], v[204:207], v[20:23]
	v_mfma_f32_16x16x32_bf16 v[16:19], v[180:183], v[204:207], v[16:19]
	v_mfma_f32_16x16x32_bf16 v[4:7], v[172:175], v[212:215], v[4:7]
	v_mfma_f32_16x16x32_bf16 v[0:3], v[180:183], v[212:215], v[0:3]
	v_mfma_f32_16x16x32_bf16 v[52:55], v[176:179], v[192:195], v[52:55]
	v_mfma_f32_16x16x32_bf16 v[48:51], v[184:187], v[192:195], v[48:51]
	v_mfma_f32_16x16x32_bf16 v[36:39], v[176:179], v[200:203], v[36:39]
	v_mfma_f32_16x16x32_bf16 v[32:35], v[184:187], v[200:203], v[32:35]
	v_mfma_f32_16x16x32_bf16 v[20:23], v[176:179], v[208:211], v[20:23]
	v_mfma_f32_16x16x32_bf16 v[16:19], v[184:187], v[208:211], v[16:19]
	v_mfma_f32_16x16x32_bf16 v[4:7], v[176:179], v[216:219], v[4:7]
	v_mfma_f32_16x16x32_bf16 v[0:3], v[184:187], v[216:219], v[0:3]
	s_setprio 0
	s_barrier
	s_add_i32 s62, s62, 2
	s_add_u32 s34, s34, 0x100
	s_addc_u32 s35, s35, 0
	s_add_u32 s60, s60, 0x100
	s_addc_u32 s61, s61, 0
	s_cmp_gt_u32 s62, 13
	s_cbranch_scc0 .LBB0_1341
	s_and_b64 vcc, exec, s[16:17]
	s_cbranch_vccz .LBB0_1344
	s_barrier
.LBB0_1344:
	s_lshl_b32 s21, s28, 8
	s_add_i32 s21, s21, s50
	v_mbcnt_lo_u32_b32 v148, -1, 0
	v_mbcnt_hi_u32_b32 v148, -1, v148
	s_nop 0
	v_and_or_b32 v144, v148, 15, s21
	v_ashrrev_i32_e32 v145, 31, v144
	v_lshl_add_u64 v[146:147], v[144:145], 2, s[6:7]
	v_lshlrev_b64 v[154:155], 13, v[144:145]
	s_lshl_b32 s21, s57, 8
	v_ashrrev_i32_e32 v146, 1, v148
	s_or_b32 s21, s21, s51
	v_and_b32_e32 v146, -8, v146
	v_add_u32_e32 v146, s21, v146
	v_ashrrev_i32_e32 v147, 31, v146
	v_lshl_add_u64 v[154:155], s[8:9], 0, v[154:155]
	v_lshlrev_b64 v[146:147], 1, v[146:147]
	v_lshl_add_u64 v[154:155], v[154:155], 0, v[146:147]
	s_waitcnt vmcnt(14)
	v_fmamk_f32 v145, v228, 0x3a800000, v159
	v_fmamk_f32 v148, v229, 0x3a800000, v159
	v_fmamk_f32 v150, v230, 0x3a800000, v159
	v_fmamk_f32 v152, v231, 0x3a800000, v159
	v_fmamk_f32 v156, v233, 0x3a800000, v159
	v_rsq_f32_e32 v160, v145
	v_fmamk_f32 v161, v234, 0x3a800000, v159
	v_fmamk_f32 v165, v235, 0x3a800000, v159
	v_fmamk_f32 v163, v238, 0x3a800000, v159
	v_pk_mul_f32 v[126:127], v[126:127], v[160:161] op_sel_hi:[1,0]
	v_pk_mul_f32 v[124:125], v[124:125], v[160:161] op_sel_hi:[1,0]
	v_pk_mul_f32 v[122:123], v[122:123], v[160:161] op_sel_hi:[1,0]
	v_pk_mul_f32 v[120:121], v[120:121], v[160:161] op_sel_hi:[1,0]
	v_pk_mul_f32 v[118:119], v[118:119], v[160:161] op_sel_hi:[1,0]
	v_pk_mul_f32 v[116:117], v[116:117], v[160:161] op_sel_hi:[1,0]
	v_pk_mul_f32 v[114:115], v[114:115], v[160:161] op_sel_hi:[1,0]
	v_pk_mul_f32 v[112:113], v[112:113], v[160:161] op_sel_hi:[1,0]
	v_max_f32_e32 v124, 0, v124
	v_max_f32_e32 v125, 0, v125
	v_max_f32_e32 v126, 0, v126
	v_max_f32_e32 v127, 0, v127
	v_max_f32_e32 v120, 0, v120
	v_max_f32_e32 v121, 0, v121
	v_max_f32_e32 v122, 0, v122
	v_max_f32_e32 v123, 0, v123
	v_max_f32_e32 v116, 0, v116
	v_max_f32_e32 v117, 0, v117
	v_max_f32_e32 v118, 0, v118
	v_max_f32_e32 v119, 0, v119
	v_max_f32_e32 v112, 0, v112
	v_max_f32_e32 v113, 0, v113
	v_max_f32_e32 v114, 0, v114
	v_max_f32_e32 v115, 0, v115
	v_pk_mul_f32 v[124:125], v[124:125], v[124:125]
	v_pk_mul_f32 v[126:127], v[126:127], v[126:127]
	v_pk_mul_f32 v[120:121], v[120:121], v[120:121]
	v_pk_mul_f32 v[122:123], v[122:123], v[122:123]
	v_rsq_f32_e32 v158, v152
	v_rsq_f32_e32 v152, v161
	v_pk_mul_f32 v[116:117], v[116:117], v[116:117]
	v_pk_mul_f32 v[118:119], v[118:119], v[118:119]
	v_pk_mul_f32 v[160:161], v[112:113], v[112:113]
	v_pk_mul_f32 v[166:167], v[114:115], v[114:115]
	v_cvt_pk_bf16_f32 v112, v124, v125
	v_cvt_pk_bf16_f32 v113, v126, v127
	v_cvt_pk_bf16_f32 v114, v120, v121
	v_cvt_pk_bf16_f32 v115, v122, v123
	v_rsq_f32_e32 v162, v148
	v_rsq_f32_e32 v164, v150
	v_rsq_f32_e32 v156, v156
	v_rsq_f32_e32 v150, v165
	v_rsq_f32_e32 v148, v163
	v_cvt_pk_bf16_f32 v116, v116, v117
	v_cvt_pk_bf16_f32 v117, v118, v119
	v_cvt_pk_bf16_f32 v118, v160, v161
	v_cvt_pk_bf16_f32 v119, v166, v167
	global_store_dwordx4 v[154:155], v[112:115], off
	global_store_dwordx4 v[154:155], v[116:119], off offset:256
	s_nop 0
	v_or_b32_e32 v112, 16, v144
	v_pk_mul_f32 v[104:105], v[104:105], v[162:163] op_sel_hi:[1,0]
	v_ashrrev_i32_e32 v113, 31, v112
; DI void st8(bf16_t* p, const float (&v)[8]) { u32x4 w; w.x = cvtpk(v[0], v[1]); w.y = cvtpk(v[2], v[3]); w.z = cvtpk(v[4], v[5]); w.w = cvtpk(v[6], v[7]); *(u32x4*)p = w; }
; #define ACC8(v, ai, bj, m, s) do { const f32x4 a_ = acc[ai][bj][m][0] * (s), b_ = acc[ai][bj][m][1] * (s); v[0] = a_[0]; v[1] = a_[1]; v[2] = a_[2]; v[3] = a_[3]; v[4] = b_[0]; v[5] = b_[1]; v[6] = b_[2]; v[7] = b_[3]; } while (0)
; #define ITLOOP _Pragma("unroll") for (int it = 0; it < 8; ++it)
; #define BJLOOP _Pragma("unroll") for (int bj = 0; bj < 2; ++bj)
; #define SBE() __builtin_amdgcn_sched_barrier(0)
;     DI void operator()(const AccT& acc, const pg8::Unit& u, int wr, int wc, int fr_in, int fq_in) const {
;     ...
;             ITLOOP { BJLOOP { float v[8]; ACC8(v, IT_AI, bj, IT_M, rs[it]);
; #pragma unroll
;                 for (int e = 0; e < 8; ++e) { const float t = fmaxf(v[e], 0.f); v[e] = t * t; }
;                 st8(b.hdn + IT_ROW * 4096 + tc0 + bj * 128, v); } SBE(); }
	v_pk_mul_f32 v[110:111], v[110:111], v[162:163] op_sel_hi:[1,0]
	v_pk_mul_f32 v[108:109], v[108:109], v[162:163] op_sel_hi:[1,0]
	v_pk_mul_f32 v[106:107], v[106:107], v[162:163] op_sel_hi:[1,0]
	v_max_f32_e32 v104, 0, v104
	v_max_f32_e32 v105, 0, v105
	v_lshlrev_b64 v[112:113], 13, v[112:113]
	v_max_f32_e32 v108, 0, v108
	v_max_f32_e32 v109, 0, v109
	v_max_f32_e32 v110, 0, v110
	v_max_f32_e32 v111, 0, v111
	v_pk_mul_f32 v[114:115], v[104:105], v[104:105]
	v_max_f32_e32 v104, 0, v106
	v_max_f32_e32 v105, 0, v107
	v_pk_mul_f32 v[108:109], v[108:109], v[108:109]
	v_pk_mul_f32 v[110:111], v[110:111], v[110:111]
	v_pk_mul_f32 v[116:117], v[104:105], v[104:105]
	v_lshl_add_u64 v[104:105], s[8:9], 0, v[112:113]
	v_pk_mul_f32 v[96:97], v[96:97], v[162:163] op_sel_hi:[1,0]
	v_lshl_add_u64 v[112:113], v[104:105], 0, v[146:147]
	v_cvt_pk_bf16_f32 v104, v108, v109
	v_cvt_pk_bf16_f32 v105, v110, v111
	v_cvt_pk_bf16_f32 v106, v114, v115
	v_cvt_pk_bf16_f32 v107, v116, v117
	v_pk_mul_f32 v[102:103], v[102:103], v[162:163] op_sel_hi:[1,0]
	v_pk_mul_f32 v[100:101], v[100:101], v[162:163] op_sel_hi:[1,0]
	v_pk_mul_f32 v[98:99], v[98:99], v[162:163] op_sel_hi:[1,0]
	v_max_f32_e32 v96, 0, v96
	v_max_f32_e32 v97, 0, v97
	global_store_dwordx4 v[112:113], v[104:107], off
	v_max_f32_e32 v100, 0, v100
	v_max_f32_e32 v101, 0, v101
	v_max_f32_e32 v102, 0, v102
	v_max_f32_e32 v103, 0, v103
	v_pk_mul_f32 v[104:105], v[96:97], v[96:97]
	v_max_f32_e32 v96, 0, v98
	v_max_f32_e32 v97, 0, v99
	v_pk_mul_f32 v[100:101], v[100:101], v[100:101]
	v_pk_mul_f32 v[102:103], v[102:103], v[102:103]
	v_pk_mul_f32 v[106:107], v[96:97], v[96:97]
	v_cvt_pk_bf16_f32 v96, v100, v101
	v_cvt_pk_bf16_f32 v97, v102, v103
	v_cvt_pk_bf16_f32 v98, v104, v105
	v_cvt_pk_bf16_f32 v99, v106, v107
	global_store_dwordx4 v[112:113], v[96:99], off offset:256
	s_nop 1
	v_or_b32_e32 v96, 32, v144
	v_pk_mul_f32 v[88:89], v[88:89], v[164:165] op_sel_hi:[1,0]
	v_ashrrev_i32_e32 v97, 31, v96
	v_pk_mul_f32 v[94:95], v[94:95], v[164:165] op_sel_hi:[1,0]
	v_pk_mul_f32 v[92:93], v[92:93], v[164:165] op_sel_hi:[1,0]
	v_pk_mul_f32 v[90:91], v[90:91], v[164:165] op_sel_hi:[1,0]
	v_max_f32_e32 v88, 0, v88
	v_max_f32_e32 v89, 0, v89
	v_lshlrev_b64 v[96:97], 13, v[96:97]
	v_max_f32_e32 v92, 0, v92
	v_max_f32_e32 v93, 0, v93
	v_max_f32_e32 v94, 0, v94
	v_max_f32_e32 v95, 0, v95
	v_pk_mul_f32 v[98:99], v[88:89], v[88:89]
	v_max_f32_e32 v88, 0, v90
	v_max_f32_e32 v89, 0, v91
	v_pk_mul_f32 v[92:93], v[92:93], v[92:93]
	v_pk_mul_f32 v[94:95], v[94:95], v[94:95]
	v_pk_mul_f32 v[100:101], v[88:89], v[88:89]
	v_lshl_add_u64 v[88:89], s[8:9], 0, v[96:97]
	v_pk_mul_f32 v[80:81], v[80:81], v[164:165] op_sel_hi:[1,0]
	v_lshl_add_u64 v[96:97], v[88:89], 0, v[146:147]
	v_cvt_pk_bf16_f32 v88, v92, v93
	v_cvt_pk_bf16_f32 v89, v94, v95
	v_cvt_pk_bf16_f32 v90, v98, v99
	v_cvt_pk_bf16_f32 v91, v100, v101
	v_pk_mul_f32 v[86:87], v[86:87], v[164:165] op_sel_hi:[1,0]
	v_pk_mul_f32 v[84:85], v[84:85], v[164:165] op_sel_hi:[1,0]
	v_pk_mul_f32 v[82:83], v[82:83], v[164:165] op_sel_hi:[1,0]
	v_max_f32_e32 v80, 0, v80
	v_max_f32_e32 v81, 0, v81
	global_store_dwordx4 v[96:97], v[88:91], off
	v_max_f32_e32 v84, 0, v84
	v_max_f32_e32 v85, 0, v85
	v_max_f32_e32 v86, 0, v86
	v_max_f32_e32 v87, 0, v87
	v_pk_mul_f32 v[88:89], v[80:81], v[80:81]
	v_max_f32_e32 v80, 0, v82
	v_max_f32_e32 v81, 0, v83
	v_pk_mul_f32 v[84:85], v[84:85], v[84:85]
	v_pk_mul_f32 v[86:87], v[86:87], v[86:87]
	v_pk_mul_f32 v[90:91], v[80:81], v[80:81]
	v_cvt_pk_bf16_f32 v80, v84, v85
	v_cvt_pk_bf16_f32 v81, v86, v87
	v_cvt_pk_bf16_f32 v82, v88, v89
	v_cvt_pk_bf16_f32 v83, v90, v91
	global_store_dwordx4 v[96:97], v[80:83], off offset:256
	s_nop 1
	v_or_b32_e32 v80, 48, v144
	v_pk_mul_f32 v[72:73], v[72:73], v[158:159] op_sel_hi:[1,0]
	v_ashrrev_i32_e32 v81, 31, v80
	v_pk_mul_f32 v[78:79], v[78:79], v[158:159] op_sel_hi:[1,0]
	v_pk_mul_f32 v[76:77], v[76:77], v[158:159] op_sel_hi:[1,0]
	v_pk_mul_f32 v[74:75], v[74:75], v[158:159] op_sel_hi:[1,0]
	v_max_f32_e32 v72, 0, v72
	v_max_f32_e32 v73, 0, v73
	v_lshlrev_b64 v[80:81], 13, v[80:81]
	v_max_f32_e32 v76, 0, v76
	v_max_f32_e32 v77, 0, v77
	v_max_f32_e32 v78, 0, v78
	v_max_f32_e32 v79, 0, v79
	v_pk_mul_f32 v[82:83], v[72:73], v[72:73]
	v_max_f32_e32 v72, 0, v74
	v_max_f32_e32 v73, 0, v75
	v_pk_mul_f32 v[76:77], v[76:77], v[76:77]
	v_pk_mul_f32 v[78:79], v[78:79], v[78:79]
	v_pk_mul_f32 v[84:85], v[72:73], v[72:73]
	v_lshl_add_u64 v[72:73], s[8:9], 0, v[80:81]
	v_pk_mul_f32 v[64:65], v[64:65], v[158:159] op_sel_hi:[1,0]
	v_lshl_add_u64 v[80:81], v[72:73], 0, v[146:147]
	v_cvt_pk_bf16_f32 v72, v76, v77
	v_cvt_pk_bf16_f32 v73, v78, v79
	v_cvt_pk_bf16_f32 v74, v82, v83
	v_cvt_pk_bf16_f32 v75, v84, v85
	v_pk_mul_f32 v[70:71], v[70:71], v[158:159] op_sel_hi:[1,0]
	v_pk_mul_f32 v[68:69], v[68:69], v[158:159] op_sel_hi:[1,0]
	v_pk_mul_f32 v[66:67], v[66:67], v[158:159] op_sel_hi:[1,0]
	v_max_f32_e32 v64, 0, v64
	v_max_f32_e32 v65, 0, v65
	global_store_dwordx4 v[80:81], v[72:75], off
	v_max_f32_e32 v68, 0, v68
	v_max_f32_e32 v69, 0, v69
	v_max_f32_e32 v70, 0, v70
	v_max_f32_e32 v71, 0, v71
	v_pk_mul_f32 v[72:73], v[64:65], v[64:65]
	v_max_f32_e32 v64, 0, v66
	v_max_f32_e32 v65, 0, v67
	v_pk_mul_f32 v[68:69], v[68:69], v[68:69]
	v_pk_mul_f32 v[70:71], v[70:71], v[70:71]
	v_pk_mul_f32 v[74:75], v[64:65], v[64:65]
	v_cvt_pk_bf16_f32 v64, v68, v69
	v_cvt_pk_bf16_f32 v65, v70, v71
	v_cvt_pk_bf16_f32 v66, v72, v73
	v_cvt_pk_bf16_f32 v67, v74, v75
	global_store_dwordx4 v[80:81], v[64:67], off offset:256
	v_pk_mul_f32 v[60:61], v[60:61], v[156:157] op_sel_hi:[1,0]
	v_pk_mul_f32 v[56:57], v[56:57], v[156:157] op_sel_hi:[1,0]
; DI void st8(bf16_t* p, const float (&v)[8]) { u32x4 w; w.x = cvtpk(v[0], v[1]); w.y = cvtpk(v[2], v[3]); w.z = cvtpk(v[4], v[5]); w.w = cvtpk(v[6], v[7]); *(u32x4*)p = w; }
; #define ACC8(v, ai, bj, m, s) do { const f32x4 a_ = acc[ai][bj][m][0] * (s), b_ = acc[ai][bj][m][1] * (s); v[0] = a_[0]; v[1] = a_[1]; v[2] = a_[2]; v[3] = a_[3]; v[4] = b_[0]; v[5] = b_[1]; v[6] = b_[2]; v[7] = b_[3]; } while (0)
; #define ITLOOP _Pragma("unroll") for (int it = 0; it < 8; ++it)
; #define BJLOOP _Pragma("unroll") for (int bj = 0; bj < 2; ++bj)
; #define SBE() __builtin_amdgcn_sched_barrier(0)
;     DI void operator()(const AccT& acc, const pg8::Unit& u, int wr, int wc, int fr_in, int fq_in) const {
;     ...
;             ITLOOP { BJLOOP { float v[8]; ACC8(v, IT_AI, bj, IT_M, rs[it]);
; #pragma unroll
;                 for (int e = 0; e < 8; ++e) { const float t = fmaxf(v[e], 0.f); v[e] = t * t; }
;                 st8(b.hdn + IT_ROW * 4096 + tc0 + bj * 128, v); } SBE(); }
	v_pk_mul_f32 v[62:63], v[62:63], v[156:157] op_sel_hi:[1,0]
	v_pk_mul_f32 v[58:59], v[58:59], v[156:157] op_sel_hi:[1,0]
	v_max_f32_e32 v60, 0, v60
	v_max_f32_e32 v61, 0, v61
	v_max_f32_e32 v56, 0, v56
	v_max_f32_e32 v57, 0, v57
	v_pk_mul_f32 v[60:61], v[60:61], v[60:61]
	v_max_f32_e32 v62, 0, v62
	v_max_f32_e32 v63, 0, v63
	v_pk_mul_f32 v[64:65], v[56:57], v[56:57]
	v_max_f32_e32 v56, 0, v58
	v_max_f32_e32 v57, 0, v59
	v_pk_mul_f32 v[62:63], v[62:63], v[62:63]
	v_pk_mul_f32 v[66:67], v[56:57], v[56:57]
	v_cvt_pk_bf16_f32 v56, v60, v61
	v_add_co_u32_e32 v60, vcc, s56, v154
	v_pk_mul_f32 v[48:49], v[48:49], v[156:157] op_sel_hi:[1,0]
	v_cvt_pk_bf16_f32 v57, v62, v63
	v_cvt_pk_bf16_f32 v58, v64, v65
	v_cvt_pk_bf16_f32 v59, v66, v67
	v_addc_co_u32_e32 v61, vcc, 0, v155, vcc
	v_pk_mul_f32 v[54:55], v[54:55], v[156:157] op_sel_hi:[1,0]
	v_pk_mul_f32 v[52:53], v[52:53], v[156:157] op_sel_hi:[1,0]
	v_pk_mul_f32 v[50:51], v[50:51], v[156:157] op_sel_hi:[1,0]
	v_max_f32_e32 v48, 0, v48
	v_max_f32_e32 v49, 0, v49
	global_store_dwordx4 v[60:61], v[56:59], off
	v_max_f32_e32 v52, 0, v52
	v_max_f32_e32 v53, 0, v53
	v_max_f32_e32 v54, 0, v54
	v_max_f32_e32 v55, 0, v55
	v_pk_mul_f32 v[56:57], v[48:49], v[48:49]
	v_max_f32_e32 v48, 0, v50
	v_max_f32_e32 v49, 0, v51
	v_pk_mul_f32 v[52:53], v[52:53], v[52:53]
	v_pk_mul_f32 v[54:55], v[54:55], v[54:55]
	v_pk_mul_f32 v[58:59], v[48:49], v[48:49]
	v_lshl_add_u64 v[68:69], v[154:155], 0, s[18:19]
	v_cvt_pk_bf16_f32 v48, v52, v53
	v_cvt_pk_bf16_f32 v49, v54, v55
	v_cvt_pk_bf16_f32 v50, v56, v57
	v_cvt_pk_bf16_f32 v51, v58, v59
	global_store_dwordx4 v[68:69], v[48:51], off offset:256
	s_nop 1
	v_add_u32_e32 v48, 0x90, v144
	v_pk_mul_f32 v[40:41], v[40:41], v[152:153] op_sel_hi:[1,0]
	v_ashrrev_i32_e32 v49, 31, v48
	v_pk_mul_f32 v[46:47], v[46:47], v[152:153] op_sel_hi:[1,0]
	v_pk_mul_f32 v[44:45], v[44:45], v[152:153] op_sel_hi:[1,0]
	v_pk_mul_f32 v[42:43], v[42:43], v[152:153] op_sel_hi:[1,0]
	v_max_f32_e32 v40, 0, v40
	v_max_f32_e32 v41, 0, v41
	v_lshlrev_b64 v[48:49], 13, v[48:49]
	v_max_f32_e32 v44, 0, v44
	v_max_f32_e32 v45, 0, v45
	v_max_f32_e32 v46, 0, v46
	v_max_f32_e32 v47, 0, v47
	v_pk_mul_f32 v[50:51], v[40:41], v[40:41]
	v_max_f32_e32 v40, 0, v42
	v_max_f32_e32 v41, 0, v43
	v_pk_mul_f32 v[44:45], v[44:45], v[44:45]
	v_pk_mul_f32 v[46:47], v[46:47], v[46:47]
	v_pk_mul_f32 v[52:53], v[40:41], v[40:41]
	v_lshl_add_u64 v[40:41], s[8:9], 0, v[48:49]
	v_pk_mul_f32 v[32:33], v[32:33], v[152:153] op_sel_hi:[1,0]
	v_lshl_add_u64 v[48:49], v[40:41], 0, v[146:147]
	v_cvt_pk_bf16_f32 v40, v44, v45
	v_cvt_pk_bf16_f32 v41, v46, v47
	v_cvt_pk_bf16_f32 v42, v50, v51
	v_cvt_pk_bf16_f32 v43, v52, v53
	v_pk_mul_f32 v[38:39], v[38:39], v[152:153] op_sel_hi:[1,0]
	v_pk_mul_f32 v[36:37], v[36:37], v[152:153] op_sel_hi:[1,0]
	v_pk_mul_f32 v[34:35], v[34:35], v[152:153] op_sel_hi:[1,0]
	v_max_f32_e32 v32, 0, v32
	v_max_f32_e32 v33, 0, v33
	global_store_dwordx4 v[48:49], v[40:43], off
	v_max_f32_e32 v36, 0, v36
	v_max_f32_e32 v37, 0, v37
	v_max_f32_e32 v38, 0, v38
	v_max_f32_e32 v39, 0, v39
	v_pk_mul_f32 v[40:41], v[32:33], v[32:33]
	v_max_f32_e32 v32, 0, v34
	v_max_f32_e32 v33, 0, v35
	v_pk_mul_f32 v[36:37], v[36:37], v[36:37]
	v_pk_mul_f32 v[38:39], v[38:39], v[38:39]
	v_pk_mul_f32 v[42:43], v[32:33], v[32:33]
	v_cvt_pk_bf16_f32 v32, v36, v37
	v_cvt_pk_bf16_f32 v33, v38, v39
	v_cvt_pk_bf16_f32 v34, v40, v41
	v_cvt_pk_bf16_f32 v35, v42, v43
	global_store_dwordx4 v[48:49], v[32:35], off offset:256
	s_nop 1
	v_add_u32_e32 v32, 0xa0, v144
	v_pk_mul_f32 v[24:25], v[24:25], v[150:151] op_sel_hi:[1,0]
	v_ashrrev_i32_e32 v33, 31, v32
; DI void st8(bf16_t* p, const float (&v)[8]) { u32x4 w; w.x = cvtpk(v[0], v[1]); w.y = cvtpk(v[2], v[3]); w.z = cvtpk(v[4], v[5]); w.w = cvtpk(v[6], v[7]); *(u32x4*)p = w; }
; #define ACC8(v, ai, bj, m, s) do { const f32x4 a_ = acc[ai][bj][m][0] * (s), b_ = acc[ai][bj][m][1] * (s); v[0] = a_[0]; v[1] = a_[1]; v[2] = a_[2]; v[3] = a_[3]; v[4] = b_[0]; v[5] = b_[1]; v[6] = b_[2]; v[7] = b_[3]; } while (0)
; #define ITLOOP _Pragma("unroll") for (int it = 0; it < 8; ++it)
; #define BJLOOP _Pragma("unroll") for (int bj = 0; bj < 2; ++bj)
; #define SBE() __builtin_amdgcn_sched_barrier(0)
;     ...
;         if (!has_next) break;
;     DI void operator()(const AccT& acc, const pg8::Unit& u, int wr, int wc, int fr_in, int fq_in) const {
;     ...
;             ITLOOP { BJLOOP { float v[8]; ACC8(v, IT_AI, bj, IT_M, rs[it]);
; #pragma unroll
;                 for (int e = 0; e < 8; ++e) { const float t = fmaxf(v[e], 0.f); v[e] = t * t; }
;                 st8(b.hdn + IT_ROW * 4096 + tc0 + bj * 128, v); } SBE(); }
	v_pk_mul_f32 v[30:31], v[30:31], v[150:151] op_sel_hi:[1,0]
	v_pk_mul_f32 v[28:29], v[28:29], v[150:151] op_sel_hi:[1,0]
	v_pk_mul_f32 v[26:27], v[26:27], v[150:151] op_sel_hi:[1,0]
	v_max_f32_e32 v24, 0, v24
	v_max_f32_e32 v25, 0, v25
	v_lshlrev_b64 v[32:33], 13, v[32:33]
	v_max_f32_e32 v28, 0, v28
	v_max_f32_e32 v29, 0, v29
	v_max_f32_e32 v30, 0, v30
	v_max_f32_e32 v31, 0, v31
	v_pk_mul_f32 v[34:35], v[24:25], v[24:25]
	v_max_f32_e32 v24, 0, v26
	v_max_f32_e32 v25, 0, v27
	v_pk_mul_f32 v[28:29], v[28:29], v[28:29]
	v_pk_mul_f32 v[30:31], v[30:31], v[30:31]
	v_pk_mul_f32 v[36:37], v[24:25], v[24:25]
	v_lshl_add_u64 v[24:25], s[8:9], 0, v[32:33]
	v_pk_mul_f32 v[16:17], v[16:17], v[150:151] op_sel_hi:[1,0]
	v_lshl_add_u64 v[32:33], v[24:25], 0, v[146:147]
	v_cvt_pk_bf16_f32 v24, v28, v29
	v_cvt_pk_bf16_f32 v25, v30, v31
	v_cvt_pk_bf16_f32 v26, v34, v35
	v_cvt_pk_bf16_f32 v27, v36, v37
	v_pk_mul_f32 v[22:23], v[22:23], v[150:151] op_sel_hi:[1,0]
	v_pk_mul_f32 v[20:21], v[20:21], v[150:151] op_sel_hi:[1,0]
	v_pk_mul_f32 v[18:19], v[18:19], v[150:151] op_sel_hi:[1,0]
	v_max_f32_e32 v16, 0, v16
	v_max_f32_e32 v17, 0, v17
	global_store_dwordx4 v[32:33], v[24:27], off
	v_max_f32_e32 v20, 0, v20
	v_max_f32_e32 v21, 0, v21
	v_max_f32_e32 v22, 0, v22
	v_max_f32_e32 v23, 0, v23
	v_pk_mul_f32 v[24:25], v[16:17], v[16:17]
	v_max_f32_e32 v16, 0, v18
	v_max_f32_e32 v17, 0, v19
	v_pk_mul_f32 v[20:21], v[20:21], v[20:21]
	v_pk_mul_f32 v[22:23], v[22:23], v[22:23]
	v_pk_mul_f32 v[26:27], v[16:17], v[16:17]
	v_cvt_pk_bf16_f32 v16, v20, v21
	v_cvt_pk_bf16_f32 v17, v22, v23
	v_cvt_pk_bf16_f32 v18, v24, v25
	v_cvt_pk_bf16_f32 v19, v26, v27
	global_store_dwordx4 v[32:33], v[16:19], off offset:256
	s_nop 1
	v_add_u32_e32 v16, 0xb0, v144
	v_pk_mul_f32 v[8:9], v[8:9], v[148:149] op_sel_hi:[1,0]
	v_ashrrev_i32_e32 v17, 31, v16
	v_pk_mul_f32 v[14:15], v[14:15], v[148:149] op_sel_hi:[1,0]
	v_pk_mul_f32 v[12:13], v[12:13], v[148:149] op_sel_hi:[1,0]
	v_pk_mul_f32 v[10:11], v[10:11], v[148:149] op_sel_hi:[1,0]
	v_max_f32_e32 v8, 0, v8
	v_max_f32_e32 v9, 0, v9
	v_lshlrev_b64 v[16:17], 13, v[16:17]
	v_max_f32_e32 v12, 0, v12
	v_max_f32_e32 v13, 0, v13
	v_max_f32_e32 v14, 0, v14
	v_max_f32_e32 v15, 0, v15
	v_pk_mul_f32 v[18:19], v[8:9], v[8:9]
	v_max_f32_e32 v8, 0, v10
	v_max_f32_e32 v9, 0, v11
	v_pk_mul_f32 v[12:13], v[12:13], v[12:13]
	v_pk_mul_f32 v[14:15], v[14:15], v[14:15]
	v_pk_mul_f32 v[20:21], v[8:9], v[8:9]
	v_lshl_add_u64 v[8:9], s[8:9], 0, v[16:17]
	v_pk_mul_f32 v[0:1], v[0:1], v[148:149] op_sel_hi:[1,0]
	v_lshl_add_u64 v[16:17], v[8:9], 0, v[146:147]
	v_cvt_pk_bf16_f32 v8, v12, v13
	v_cvt_pk_bf16_f32 v9, v14, v15
	v_cvt_pk_bf16_f32 v10, v18, v19
	v_cvt_pk_bf16_f32 v11, v20, v21
	v_pk_mul_f32 v[6:7], v[6:7], v[148:149] op_sel_hi:[1,0]
	v_pk_mul_f32 v[4:5], v[4:5], v[148:149] op_sel_hi:[1,0]
	v_pk_mul_f32 v[2:3], v[2:3], v[148:149] op_sel_hi:[1,0]
	v_max_f32_e32 v0, 0, v0
	v_max_f32_e32 v1, 0, v1
	global_store_dwordx4 v[16:17], v[8:11], off
	v_max_f32_e32 v4, 0, v4
	v_max_f32_e32 v5, 0, v5
	v_max_f32_e32 v6, 0, v6
	v_max_f32_e32 v7, 0, v7
	v_pk_mul_f32 v[8:9], v[0:1], v[0:1]
	v_max_f32_e32 v0, 0, v2
	v_max_f32_e32 v1, 0, v3
	v_pk_mul_f32 v[4:5], v[4:5], v[4:5]
	v_pk_mul_f32 v[6:7], v[6:7], v[6:7]
	v_pk_mul_f32 v[10:11], v[0:1], v[0:1]
	v_cvt_pk_bf16_f32 v0, v4, v5
	v_cvt_pk_bf16_f32 v1, v6, v7
	v_cvt_pk_bf16_f32 v2, v8, v9
	v_cvt_pk_bf16_f32 v3, v10, v11
	global_store_dwordx4 v[16:17], v[0:3], off offset:256
	s_waitcnt vmcnt(16)
	s_barrier
	s_andn2_b64 vcc, exec, s[0:1]
	s_mov_b64 s[0:1], -1
	s_cbranch_vccnz .LBB0_1333
	s_andn2_b64 vcc, exec, s[4:5]
	s_cbranch_vccnz .LBB0_1332
	s_barrier
	s_branch .LBB0_1332
